# GEMM loops: MFMA block starts right behind its opening barrier (priority raise/drop and the repeated lgkmcnt(0) removed)
# speedup vs baseline: 1.0218x; 1.0014x over previous
.LBB0_178:
	s_add_u32 s26, s22, 0xfffc0080
	s_addc_u32 s27, s23, -1
	s_add_i32 s34, 0, 0x10000
	s_cmp_eq_u32 s59, 12
	s_cselect_b32 s31, s9, s27
	s_cselect_b32 s30, s15, s26
	s_cselect_b32 s27, s13, s58
	s_cselect_b32 s26, s56, s57
	s_add_i32 s35, 0, 0x14000
	v_add_u32_e32 v140, s34, v195
	v_add_u32_e32 v166, s35, v195
	ds_read_b128 v[128:131], v140
	ds_read_b128 v[132:135], v140 offset:1024
	ds_read_b128 v[136:139], v140 offset:2048
	ds_read_b128 v[140:143], v140 offset:3072
	ds_read_b128 v[144:147], v166
	ds_read_b128 v[148:151], v166 offset:1024
	ds_read_b128 v[180:183], v166 offset:2048
	ds_read_b128 v[184:187], v166 offset:3072
	s_add_i32 m0, s49, 0xc000
	ds_read_b128 v[188:191], v200
	ds_read_b128 v[202:205], v200 offset:1024
	ds_read_b128 v[206:209], v200 offset:2048
	ds_read_b128 v[210:213], v200 offset:3072
	ds_read_b128 v[228:231], v200 offset:4096
	ds_read_b128 v[232:235], v200 offset:5120
	ds_read_b128 v[236:239], v200 offset:6144
	ds_read_b128 v[240:243], v200 offset:7168
	global_load_lds_dwordx4 v160, s[22:23]
	s_add_i32 m0, s49, 0xe000
	s_nop 0
	global_load_lds_dwordx4 v162, s[22:23]
	s_waitcnt vmcnt(8)
	s_waitcnt lgkmcnt(0)
	s_barrier
	v_mfma_f32_16x16x32_bf16 v[124:127], v[128:131], v[188:191], v[124:127]
	v_mfma_f32_16x16x32_bf16 v[124:127], v[132:135], v[202:205], v[124:127]
	v_mfma_f32_16x16x32_bf16 v[120:123], v[140:143], v[202:205], v[120:123]
	v_mfma_f32_16x16x32_bf16 v[120:123], v[136:139], v[188:191], v[120:123]
	v_mfma_f32_16x16x32_bf16 v[116:119], v[144:147], v[188:191], v[116:119]
	v_mfma_f32_16x16x32_bf16 v[116:119], v[148:151], v[202:205], v[116:119]
	v_mfma_f32_16x16x32_bf16 v[108:111], v[184:187], v[202:205], v[108:111]
	v_mfma_f32_16x16x32_bf16 v[108:111], v[180:183], v[188:191], v[108:111]
	v_mfma_f32_16x16x32_bf16 v[92:95], v[180:183], v[206:209], v[92:95]
	v_mfma_f32_16x16x32_bf16 v[92:95], v[184:187], v[210:213], v[92:95]
	v_mfma_f32_16x16x32_bf16 v[100:103], v[148:151], v[210:213], v[100:103]
	v_mfma_f32_16x16x32_bf16 v[100:103], v[144:147], v[206:209], v[100:103]
	v_mfma_f32_16x16x32_bf16 v[104:107], v[136:139], v[206:209], v[104:107]
	v_mfma_f32_16x16x32_bf16 v[104:107], v[140:143], v[210:213], v[104:107]
	v_mfma_f32_16x16x32_bf16 v[112:115], v[132:135], v[210:213], v[112:115]
	v_mfma_f32_16x16x32_bf16 v[112:115], v[128:131], v[206:209], v[112:115]
	v_mfma_f32_16x16x32_bf16 v[96:99], v[128:131], v[228:231], v[96:99]
	v_mfma_f32_16x16x32_bf16 v[96:99], v[132:135], v[232:235], v[96:99]
	v_mfma_f32_16x16x32_bf16 v[88:91], v[140:143], v[232:235], v[88:91]
	v_mfma_f32_16x16x32_bf16 v[88:91], v[136:139], v[228:231], v[88:91]
	v_mfma_f32_16x16x32_bf16 v[84:87], v[144:147], v[228:231], v[84:87]
	v_mfma_f32_16x16x32_bf16 v[84:87], v[148:151], v[232:235], v[84:87]
	v_mfma_f32_16x16x32_bf16 v[76:79], v[184:187], v[232:235], v[76:79]
	v_mfma_f32_16x16x32_bf16 v[76:79], v[180:183], v[228:231], v[76:79]
	v_mfma_f32_16x16x32_bf16 v[64:67], v[180:183], v[236:239], v[64:67]
	v_mfma_f32_16x16x32_bf16 v[64:67], v[184:187], v[240:243], v[64:67]
	v_mfma_f32_16x16x32_bf16 v[68:71], v[148:151], v[240:243], v[68:71]
	v_mfma_f32_16x16x32_bf16 v[68:71], v[144:147], v[236:239], v[68:71]
	v_mfma_f32_16x16x32_bf16 v[72:75], v[136:139], v[236:239], v[72:75]
	v_mfma_f32_16x16x32_bf16 v[72:75], v[140:143], v[240:243], v[72:75]
	v_mfma_f32_16x16x32_bf16 v[80:83], v[132:135], v[240:243], v[80:83]
	v_mfma_f32_16x16x32_bf16 v[80:83], v[128:131], v[236:239], v[80:83]
	s_barrier
	s_add_i32 s34, s34, s45
	s_add_u32 s98, s26, s20
	s_addc_u32 s99, s27, s21
	s_mov_b32 m0, s34
	ds_read_b128 v[188:191], v200 offset:16384
	ds_read_b128 v[202:205], v200 offset:17408
	ds_read_b128 v[206:209], v200 offset:18432
	ds_read_b128 v[210:213], v200 offset:19456
	ds_read_b128 v[228:231], v200 offset:20480
	ds_read_b128 v[232:235], v200 offset:21504
	ds_read_b128 v[236:239], v200 offset:22528
	ds_read_b128 v[240:243], v200 offset:23552
	global_load_lds_dwordx4 v168, s[26:27]
	s_add_i32 m0, s34, 0x2000
	s_add_u32 s36, s26, 0x40000
	s_addc_u32 s37, s27, 0
	s_add_i32 s34, s35, s45
	global_load_lds_dwordx4 v152, s[26:27]
	s_mov_b32 m0, s34
	s_nop 0
	global_load_lds_dwordx4 v168, s[36:37]
	s_add_i32 m0, s34, 0x2000
	s_nop 0
	global_load_lds_dwordx4 v152, s[36:37]
	s_add_u32 s100, s30, s20
	s_addc_u32 s101, s31, s21
	s_mov_b32 m0, s49
	s_nop 0
	global_load_lds_dwordx4 v156, s[30:31]
	s_mov_b32 m0, s50
	s_nop 0
	global_load_lds_dwordx4 v154, s[30:31]
	s_waitcnt vmcnt(8)
	s_waitcnt lgkmcnt(0)
	s_barrier
	v_mfma_f32_16x16x32_bf16 v[60:63], v[128:131], v[188:191], v[60:63]
	v_mfma_f32_16x16x32_bf16 v[60:63], v[132:135], v[202:205], v[60:63]
	v_mfma_f32_16x16x32_bf16 v[56:59], v[140:143], v[202:205], v[56:59]
	v_mfma_f32_16x16x32_bf16 v[56:59], v[136:139], v[188:191], v[56:59]
	v_mfma_f32_16x16x32_bf16 v[52:55], v[144:147], v[188:191], v[52:55]
	v_mfma_f32_16x16x32_bf16 v[52:55], v[148:151], v[202:205], v[52:55]
	v_mfma_f32_16x16x32_bf16 v[44:47], v[184:187], v[202:205], v[44:47]
	v_mfma_f32_16x16x32_bf16 v[44:47], v[180:183], v[188:191], v[44:47]
	v_mfma_f32_16x16x32_bf16 v[28:31], v[180:183], v[206:209], v[28:31]
	v_mfma_f32_16x16x32_bf16 v[28:31], v[184:187], v[210:213], v[28:31]
	v_mfma_f32_16x16x32_bf16 v[36:39], v[148:151], v[210:213], v[36:39]
	v_mfma_f32_16x16x32_bf16 v[36:39], v[144:147], v[206:209], v[36:39]
	v_mfma_f32_16x16x32_bf16 v[40:43], v[136:139], v[206:209], v[40:43]
	v_mfma_f32_16x16x32_bf16 v[40:43], v[140:143], v[210:213], v[40:43]
	v_mfma_f32_16x16x32_bf16 v[48:51], v[132:135], v[210:213], v[48:51]
	v_mfma_f32_16x16x32_bf16 v[48:51], v[128:131], v[206:209], v[48:51]
	v_mfma_f32_16x16x32_bf16 v[32:35], v[128:131], v[228:231], v[32:35]
	v_mfma_f32_16x16x32_bf16 v[32:35], v[132:135], v[232:235], v[32:35]
	v_mfma_f32_16x16x32_bf16 v[24:27], v[140:143], v[232:235], v[24:27]
	v_mfma_f32_16x16x32_bf16 v[24:27], v[136:139], v[228:231], v[24:27]
	v_mfma_f32_16x16x32_bf16 v[20:23], v[144:147], v[228:231], v[20:23]
	v_mfma_f32_16x16x32_bf16 v[20:23], v[148:151], v[232:235], v[20:23]
	v_mfma_f32_16x16x32_bf16 v[12:15], v[184:187], v[232:235], v[12:15]
	v_mfma_f32_16x16x32_bf16 v[12:15], v[180:183], v[228:231], v[12:15]
	v_mfma_f32_16x16x32_bf16 v[0:3], v[180:183], v[236:239], v[0:3]
	v_mfma_f32_16x16x32_bf16 v[0:3], v[184:187], v[240:243], v[0:3]
	v_mfma_f32_16x16x32_bf16 v[4:7], v[148:151], v[240:243], v[4:7]
	v_mfma_f32_16x16x32_bf16 v[4:7], v[144:147], v[236:239], v[4:7]
	v_mfma_f32_16x16x32_bf16 v[8:11], v[136:139], v[236:239], v[8:11]
	v_mfma_f32_16x16x32_bf16 v[8:11], v[140:143], v[240:243], v[8:11]
	v_mfma_f32_16x16x32_bf16 v[16:19], v[132:135], v[240:243], v[16:19]
	v_mfma_f32_16x16x32_bf16 v[16:19], v[128:131], v[236:239], v[16:19]
	s_barrier
	s_add_i32 s34, 0, 0x18000
	s_add_i32 s35, 0, 0x1c000
	v_add_u32_e32 v140, s34, v195
	v_add_u32_e32 v184, s35, v195
	ds_read_b128 v[128:131], v140
	ds_read_b128 v[132:135], v140 offset:1024
	ds_read_b128 v[136:139], v140 offset:2048
	ds_read_b128 v[140:143], v140 offset:3072
	ds_read_b128 v[144:147], v184
	ds_read_b128 v[148:151], v184 offset:1024
	ds_read_b128 v[180:183], v184 offset:2048
	ds_read_b128 v[184:187], v184 offset:3072
	s_add_u32 s30, s30, 0x40000
	s_addc_u32 s31, s31, 0
	s_mov_b32 m0, s51
	ds_read_b128 v[188:191], v200 offset:32768
	ds_read_b128 v[202:205], v200 offset:33792
	ds_read_b128 v[206:209], v200 offset:34816
	ds_read_b128 v[210:213], v200 offset:35840
	ds_read_b128 v[228:231], v200 offset:36864
	ds_read_b128 v[232:235], v200 offset:37888
	ds_read_b128 v[236:239], v200 offset:38912
	ds_read_b128 v[240:243], v200 offset:39936
	global_load_lds_dwordx4 v156, s[30:31]
	s_mov_b32 m0, s52
	s_nop 0
	global_load_lds_dwordx4 v154, s[30:31]
	s_waitcnt vmcnt(8)
	s_waitcnt lgkmcnt(0)
	s_barrier
	v_mfma_f32_16x16x32_bf16 v[124:127], v[128:131], v[188:191], v[124:127]
	v_mfma_f32_16x16x32_bf16 v[124:127], v[132:135], v[202:205], v[124:127]
	v_mfma_f32_16x16x32_bf16 v[120:123], v[140:143], v[202:205], v[120:123]
	v_mfma_f32_16x16x32_bf16 v[120:123], v[136:139], v[188:191], v[120:123]
	v_mfma_f32_16x16x32_bf16 v[116:119], v[144:147], v[188:191], v[116:119]
	v_mfma_f32_16x16x32_bf16 v[116:119], v[148:151], v[202:205], v[116:119]
	v_mfma_f32_16x16x32_bf16 v[108:111], v[184:187], v[202:205], v[108:111]
	v_mfma_f32_16x16x32_bf16 v[108:111], v[180:183], v[188:191], v[108:111]
	v_mfma_f32_16x16x32_bf16 v[92:95], v[180:183], v[206:209], v[92:95]
	v_mfma_f32_16x16x32_bf16 v[92:95], v[184:187], v[210:213], v[92:95]
	v_mfma_f32_16x16x32_bf16 v[100:103], v[148:151], v[210:213], v[100:103]
	v_mfma_f32_16x16x32_bf16 v[100:103], v[144:147], v[206:209], v[100:103]
	v_mfma_f32_16x16x32_bf16 v[104:107], v[136:139], v[206:209], v[104:107]
	v_mfma_f32_16x16x32_bf16 v[104:107], v[140:143], v[210:213], v[104:107]
	v_mfma_f32_16x16x32_bf16 v[112:115], v[132:135], v[210:213], v[112:115]
	v_mfma_f32_16x16x32_bf16 v[112:115], v[128:131], v[206:209], v[112:115]
	v_mfma_f32_16x16x32_bf16 v[96:99], v[128:131], v[228:231], v[96:99]
	v_mfma_f32_16x16x32_bf16 v[96:99], v[132:135], v[232:235], v[96:99]
	v_mfma_f32_16x16x32_bf16 v[88:91], v[140:143], v[232:235], v[88:91]
	v_mfma_f32_16x16x32_bf16 v[88:91], v[136:139], v[228:231], v[88:91]
	v_mfma_f32_16x16x32_bf16 v[84:87], v[144:147], v[228:231], v[84:87]
	v_mfma_f32_16x16x32_bf16 v[84:87], v[148:151], v[232:235], v[84:87]
	v_mfma_f32_16x16x32_bf16 v[76:79], v[184:187], v[232:235], v[76:79]
	v_mfma_f32_16x16x32_bf16 v[76:79], v[180:183], v[228:231], v[76:79]
	v_mfma_f32_16x16x32_bf16 v[64:67], v[180:183], v[236:239], v[64:67]
	v_mfma_f32_16x16x32_bf16 v[64:67], v[184:187], v[240:243], v[64:67]
	v_mfma_f32_16x16x32_bf16 v[68:71], v[148:151], v[240:243], v[68:71]
	v_mfma_f32_16x16x32_bf16 v[68:71], v[144:147], v[236:239], v[68:71]
	v_mfma_f32_16x16x32_bf16 v[72:75], v[136:139], v[236:239], v[72:75]
	v_mfma_f32_16x16x32_bf16 v[72:75], v[140:143], v[240:243], v[72:75]
	v_mfma_f32_16x16x32_bf16 v[80:83], v[132:135], v[240:243], v[80:83]
	v_mfma_f32_16x16x32_bf16 v[80:83], v[128:131], v[236:239], v[80:83]
	s_barrier
	s_add_i32 s30, s34, s45
	s_mov_b32 m0, s30
	ds_read_b128 v[188:191], v200 offset:49152
	ds_read_b128 v[202:205], v200 offset:50176
	ds_read_b128 v[206:209], v200 offset:51200
	ds_read_b128 v[210:213], v200 offset:52224
	ds_read_b128 v[228:231], v200 offset:53248
	ds_read_b128 v[232:235], v200 offset:54272
	ds_read_b128 v[236:239], v200 offset:55296
	ds_read_b128 v[240:243], v200 offset:56320
	global_load_lds_dwordx4 v168, s[98:99]
	s_add_i32 m0, s30, 0x2000
	s_add_u32 s26, s26, 0x40080
	s_addc_u32 s27, s27, 0
	s_add_i32 s30, s35, s45
	global_load_lds_dwordx4 v152, s[98:99]
	s_mov_b32 m0, s30
	s_nop 0
	global_load_lds_dwordx4 v168, s[26:27]
	s_add_i32 m0, s30, 0x2000
	s_nop 0
	global_load_lds_dwordx4 v152, s[26:27]
	s_mov_b32 m0, s24
	s_nop 0
	global_load_lds_dwordx4 v156, s[100:101]
	s_mov_b32 m0, s53
	s_nop 0
	global_load_lds_dwordx4 v154, s[100:101]
	s_waitcnt vmcnt(8)
	s_waitcnt lgkmcnt(0)
	s_barrier
	v_mfma_f32_16x16x32_bf16 v[60:63], v[128:131], v[188:191], v[60:63]
	v_mfma_f32_16x16x32_bf16 v[60:63], v[132:135], v[202:205], v[60:63]
	v_mfma_f32_16x16x32_bf16 v[56:59], v[140:143], v[202:205], v[56:59]
	v_mfma_f32_16x16x32_bf16 v[56:59], v[136:139], v[188:191], v[56:59]
	v_mfma_f32_16x16x32_bf16 v[52:55], v[144:147], v[188:191], v[52:55]
	v_mfma_f32_16x16x32_bf16 v[52:55], v[148:151], v[202:205], v[52:55]
	v_mfma_f32_16x16x32_bf16 v[44:47], v[184:187], v[202:205], v[44:47]
	v_mfma_f32_16x16x32_bf16 v[44:47], v[180:183], v[188:191], v[44:47]
	v_mfma_f32_16x16x32_bf16 v[28:31], v[180:183], v[206:209], v[28:31]
	v_mfma_f32_16x16x32_bf16 v[28:31], v[184:187], v[210:213], v[28:31]
	v_mfma_f32_16x16x32_bf16 v[36:39], v[148:151], v[210:213], v[36:39]
	v_mfma_f32_16x16x32_bf16 v[36:39], v[144:147], v[206:209], v[36:39]
	v_mfma_f32_16x16x32_bf16 v[40:43], v[136:139], v[206:209], v[40:43]
	v_mfma_f32_16x16x32_bf16 v[40:43], v[140:143], v[210:213], v[40:43]
	v_mfma_f32_16x16x32_bf16 v[48:51], v[132:135], v[210:213], v[48:51]
	v_mfma_f32_16x16x32_bf16 v[48:51], v[128:131], v[206:209], v[48:51]
	v_mfma_f32_16x16x32_bf16 v[32:35], v[128:131], v[228:231], v[32:35]
	v_mfma_f32_16x16x32_bf16 v[32:35], v[132:135], v[232:235], v[32:35]
	v_mfma_f32_16x16x32_bf16 v[24:27], v[140:143], v[232:235], v[24:27]
	v_mfma_f32_16x16x32_bf16 v[24:27], v[136:139], v[228:231], v[24:27]
	v_mfma_f32_16x16x32_bf16 v[20:23], v[144:147], v[228:231], v[20:23]
	v_mfma_f32_16x16x32_bf16 v[20:23], v[148:151], v[232:235], v[20:23]
	v_mfma_f32_16x16x32_bf16 v[12:15], v[184:187], v[232:235], v[12:15]
	v_mfma_f32_16x16x32_bf16 v[12:15], v[180:183], v[228:231], v[12:15]
	v_mfma_f32_16x16x32_bf16 v[0:3], v[180:183], v[236:239], v[0:3]
	v_mfma_f32_16x16x32_bf16 v[0:3], v[184:187], v[240:243], v[0:3]
	v_mfma_f32_16x16x32_bf16 v[4:7], v[148:151], v[240:243], v[4:7]
	v_mfma_f32_16x16x32_bf16 v[4:7], v[144:147], v[236:239], v[4:7]
	v_mfma_f32_16x16x32_bf16 v[8:11], v[136:139], v[236:239], v[8:11]
	v_mfma_f32_16x16x32_bf16 v[8:11], v[140:143], v[240:243], v[8:11]
	v_mfma_f32_16x16x32_bf16 v[16:19], v[132:135], v[240:243], v[16:19]
	v_mfma_f32_16x16x32_bf16 v[16:19], v[128:131], v[236:239], v[16:19]
	s_barrier
	s_add_i32 s59, s59, 2
	s_add_u32 s22, s22, 0x100
	s_addc_u32 s23, s23, 0
	s_add_u32 s57, s57, 0x100
	s_addc_u32 s58, s58, 0
	s_cmp_gt_u32 s59, 13
	s_cbranch_scc0 .LBB0_178
	s_and_b64 vcc, exec, s[10:11]
	s_cbranch_vccz .LBB0_181
	s_barrier

.LBB0_776:
	s_add_u32 s26, s22, 0xfffc0080
	s_addc_u32 s27, s23, -1
	s_add_i32 s36, 0, 0x10000
	s_cmp_eq_u32 s55, 12
	s_cselect_b32 s31, s15, s27
	s_cselect_b32 s30, s51, s26
	s_cselect_b32 s27, s13, s54
	s_cselect_b32 s26, s52, s53
	s_add_i32 s56, 0, 0x14000
	v_add_u32_e32 v140, s36, v204
	v_add_u32_e32 v156, s56, v204
	ds_read_b128 v[128:131], v140
	ds_read_b128 v[132:135], v140 offset:1024
	ds_read_b128 v[136:139], v140 offset:2048
	ds_read_b128 v[140:143], v140 offset:3072
	ds_read_b128 v[144:147], v156
	ds_read_b128 v[148:151], v156 offset:1024
	ds_read_b128 v[152:155], v156 offset:2048
	ds_read_b128 v[156:159], v156 offset:3072
	s_add_i32 m0, s42, 0xc000
	ds_read_b128 v[182:185], v206
	ds_read_b128 v[186:189], v206 offset:1024
	ds_read_b128 v[190:193], v206 offset:2048
	ds_read_b128 v[194:197], v206 offset:3072
	ds_read_b128 v[198:201], v206 offset:4096
	ds_read_b128 v[208:211], v206 offset:5120
	ds_read_b128 v[212:215], v206 offset:6144
	ds_read_b128 v[228:231], v206 offset:7168
	global_load_lds_dwordx4 v166, s[22:23]
	s_add_i32 m0, s42, 0xe000
	s_nop 0
	global_load_lds_dwordx4 v180, s[22:23]
	s_waitcnt vmcnt(8)
	s_waitcnt lgkmcnt(0)
	s_barrier
	v_mfma_f32_16x16x32_bf16 v[124:127], v[128:131], v[182:185], v[124:127]
	v_mfma_f32_16x16x32_bf16 v[124:127], v[132:135], v[186:189], v[124:127]
	v_mfma_f32_16x16x32_bf16 v[120:123], v[140:143], v[186:189], v[120:123]
	v_mfma_f32_16x16x32_bf16 v[120:123], v[136:139], v[182:185], v[120:123]
	v_mfma_f32_16x16x32_bf16 v[116:119], v[144:147], v[182:185], v[116:119]
	v_mfma_f32_16x16x32_bf16 v[116:119], v[148:151], v[186:189], v[116:119]
	v_mfma_f32_16x16x32_bf16 v[112:115], v[156:159], v[186:189], v[112:115]
	v_mfma_f32_16x16x32_bf16 v[112:115], v[152:155], v[182:185], v[112:115]
	v_mfma_f32_16x16x32_bf16 v[96:99], v[152:155], v[190:193], v[96:99]
	v_mfma_f32_16x16x32_bf16 v[96:99], v[156:159], v[194:197], v[96:99]
	v_mfma_f32_16x16x32_bf16 v[100:103], v[148:151], v[194:197], v[100:103]
	v_mfma_f32_16x16x32_bf16 v[100:103], v[144:147], v[190:193], v[100:103]
	v_mfma_f32_16x16x32_bf16 v[104:107], v[136:139], v[190:193], v[104:107]
	v_mfma_f32_16x16x32_bf16 v[104:107], v[140:143], v[194:197], v[104:107]
	v_mfma_f32_16x16x32_bf16 v[108:111], v[132:135], v[194:197], v[108:111]
	v_mfma_f32_16x16x32_bf16 v[108:111], v[128:131], v[190:193], v[108:111]
	v_mfma_f32_16x16x32_bf16 v[92:95], v[128:131], v[198:201], v[92:95]
	v_mfma_f32_16x16x32_bf16 v[92:95], v[132:135], v[208:211], v[92:95]
	v_mfma_f32_16x16x32_bf16 v[88:91], v[140:143], v[208:211], v[88:91]
	v_mfma_f32_16x16x32_bf16 v[88:91], v[136:139], v[198:201], v[88:91]
	v_mfma_f32_16x16x32_bf16 v[84:87], v[144:147], v[198:201], v[84:87]
	v_mfma_f32_16x16x32_bf16 v[84:87], v[148:151], v[208:211], v[84:87]
	v_mfma_f32_16x16x32_bf16 v[80:83], v[156:159], v[208:211], v[80:83]
	v_mfma_f32_16x16x32_bf16 v[80:83], v[152:155], v[198:201], v[80:83]
	v_mfma_f32_16x16x32_bf16 v[64:67], v[152:155], v[212:215], v[64:67]
	v_mfma_f32_16x16x32_bf16 v[64:67], v[156:159], v[228:231], v[64:67]
	v_mfma_f32_16x16x32_bf16 v[68:71], v[148:151], v[228:231], v[68:71]
	v_mfma_f32_16x16x32_bf16 v[68:71], v[144:147], v[212:215], v[68:71]
	v_mfma_f32_16x16x32_bf16 v[72:75], v[136:139], v[212:215], v[72:75]
	v_mfma_f32_16x16x32_bf16 v[72:75], v[140:143], v[228:231], v[72:75]
	v_mfma_f32_16x16x32_bf16 v[76:79], v[132:135], v[228:231], v[76:79]
	v_mfma_f32_16x16x32_bf16 v[76:79], v[128:131], v[212:215], v[76:79]
	s_barrier
	s_add_i32 s36, s36, s35
	s_add_u32 s98, s26, s20
	s_addc_u32 s99, s27, s21
	s_mov_b32 m0, s36
	ds_read_b128 v[182:185], v206 offset:16384
	ds_read_b128 v[186:189], v206 offset:17408
	ds_read_b128 v[190:193], v206 offset:18432
	ds_read_b128 v[194:197], v206 offset:19456
	ds_read_b128 v[198:201], v206 offset:20480
	ds_read_b128 v[208:211], v206 offset:21504
	ds_read_b128 v[212:215], v206 offset:22528
	ds_read_b128 v[228:231], v206 offset:23552
	global_load_lds_dwordx4 v168, s[26:27]
	s_add_i32 m0, s36, 0x2000
	s_add_u32 s36, s26, 0x40000
	s_addc_u32 s37, s27, 0
	s_add_i32 s56, s56, s35
	global_load_lds_dwordx4 v160, s[26:27]
	s_mov_b32 m0, s56
	s_nop 0
	global_load_lds_dwordx4 v168, s[36:37]
	s_add_i32 m0, s56, 0x2000
	s_nop 0
	global_load_lds_dwordx4 v160, s[36:37]
	s_add_u32 s100, s30, s20
	s_addc_u32 s101, s31, s21
	s_mov_b32 m0, s42
	s_nop 0
	global_load_lds_dwordx4 v164, s[30:31]
	s_mov_b32 m0, s43
	s_nop 0
	global_load_lds_dwordx4 v162, s[30:31]
	s_waitcnt vmcnt(8)
	s_waitcnt lgkmcnt(0)
	s_barrier
	v_mfma_f32_16x16x32_bf16 v[60:63], v[128:131], v[182:185], v[60:63]
	v_mfma_f32_16x16x32_bf16 v[60:63], v[132:135], v[186:189], v[60:63]
	v_mfma_f32_16x16x32_bf16 v[56:59], v[140:143], v[186:189], v[56:59]
	v_mfma_f32_16x16x32_bf16 v[56:59], v[136:139], v[182:185], v[56:59]
	v_mfma_f32_16x16x32_bf16 v[52:55], v[144:147], v[182:185], v[52:55]
	v_mfma_f32_16x16x32_bf16 v[52:55], v[148:151], v[186:189], v[52:55]
	v_mfma_f32_16x16x32_bf16 v[48:51], v[156:159], v[186:189], v[48:51]
	v_mfma_f32_16x16x32_bf16 v[48:51], v[152:155], v[182:185], v[48:51]
	v_mfma_f32_16x16x32_bf16 v[32:35], v[152:155], v[190:193], v[32:35]
	v_mfma_f32_16x16x32_bf16 v[32:35], v[156:159], v[194:197], v[32:35]
	v_mfma_f32_16x16x32_bf16 v[36:39], v[148:151], v[194:197], v[36:39]
	v_mfma_f32_16x16x32_bf16 v[36:39], v[144:147], v[190:193], v[36:39]
	v_mfma_f32_16x16x32_bf16 v[40:43], v[136:139], v[190:193], v[40:43]
	v_mfma_f32_16x16x32_bf16 v[40:43], v[140:143], v[194:197], v[40:43]
	v_mfma_f32_16x16x32_bf16 v[44:47], v[132:135], v[194:197], v[44:47]
	v_mfma_f32_16x16x32_bf16 v[44:47], v[128:131], v[190:193], v[44:47]
	v_mfma_f32_16x16x32_bf16 v[28:31], v[128:131], v[198:201], v[28:31]
	v_mfma_f32_16x16x32_bf16 v[28:31], v[132:135], v[208:211], v[28:31]
	v_mfma_f32_16x16x32_bf16 v[24:27], v[140:143], v[208:211], v[24:27]
	v_mfma_f32_16x16x32_bf16 v[24:27], v[136:139], v[198:201], v[24:27]
	v_mfma_f32_16x16x32_bf16 v[20:23], v[144:147], v[198:201], v[20:23]
	v_mfma_f32_16x16x32_bf16 v[20:23], v[148:151], v[208:211], v[20:23]
	v_mfma_f32_16x16x32_bf16 v[16:19], v[156:159], v[208:211], v[16:19]
	v_mfma_f32_16x16x32_bf16 v[16:19], v[152:155], v[198:201], v[16:19]
	v_mfma_f32_16x16x32_bf16 v[0:3], v[152:155], v[212:215], v[0:3]
	v_mfma_f32_16x16x32_bf16 v[0:3], v[156:159], v[228:231], v[0:3]
	v_mfma_f32_16x16x32_bf16 v[4:7], v[148:151], v[228:231], v[4:7]
	v_mfma_f32_16x16x32_bf16 v[4:7], v[144:147], v[212:215], v[4:7]
	v_mfma_f32_16x16x32_bf16 v[8:11], v[136:139], v[212:215], v[8:11]
	v_mfma_f32_16x16x32_bf16 v[8:11], v[140:143], v[228:231], v[8:11]
	v_mfma_f32_16x16x32_bf16 v[12:15], v[132:135], v[228:231], v[12:15]
	v_mfma_f32_16x16x32_bf16 v[12:15], v[128:131], v[212:215], v[12:15]
	s_barrier
	s_add_i32 s36, 0, 0x18000
	s_add_i32 s37, 0, 0x1c000
	v_add_u32_e32 v140, s36, v204
	v_add_u32_e32 v156, s37, v204
	ds_read_b128 v[128:131], v140
	ds_read_b128 v[132:135], v140 offset:1024
	ds_read_b128 v[136:139], v140 offset:2048
	ds_read_b128 v[140:143], v140 offset:3072
	ds_read_b128 v[144:147], v156
	ds_read_b128 v[148:151], v156 offset:1024
	ds_read_b128 v[152:155], v156 offset:2048
	ds_read_b128 v[156:159], v156 offset:3072
	s_add_u32 s30, s30, 0x40000
	s_addc_u32 s31, s31, 0
	s_mov_b32 m0, s44
	ds_read_b128 v[182:185], v206 offset:32768
	ds_read_b128 v[186:189], v206 offset:33792
	ds_read_b128 v[190:193], v206 offset:34816
	ds_read_b128 v[194:197], v206 offset:35840
	ds_read_b128 v[198:201], v206 offset:36864
	ds_read_b128 v[208:211], v206 offset:37888
	ds_read_b128 v[212:215], v206 offset:38912
	ds_read_b128 v[228:231], v206 offset:39936
	global_load_lds_dwordx4 v164, s[30:31]
	s_mov_b32 m0, s45
	s_nop 0
	global_load_lds_dwordx4 v162, s[30:31]
	s_waitcnt vmcnt(8)
	s_waitcnt lgkmcnt(0)
	s_barrier
	v_mfma_f32_16x16x32_bf16 v[124:127], v[128:131], v[182:185], v[124:127]
	v_mfma_f32_16x16x32_bf16 v[124:127], v[132:135], v[186:189], v[124:127]
	v_mfma_f32_16x16x32_bf16 v[120:123], v[140:143], v[186:189], v[120:123]
	v_mfma_f32_16x16x32_bf16 v[120:123], v[136:139], v[182:185], v[120:123]
	v_mfma_f32_16x16x32_bf16 v[116:119], v[144:147], v[182:185], v[116:119]
	v_mfma_f32_16x16x32_bf16 v[116:119], v[148:151], v[186:189], v[116:119]
	v_mfma_f32_16x16x32_bf16 v[112:115], v[156:159], v[186:189], v[112:115]
	v_mfma_f32_16x16x32_bf16 v[112:115], v[152:155], v[182:185], v[112:115]
	v_mfma_f32_16x16x32_bf16 v[96:99], v[152:155], v[190:193], v[96:99]
	v_mfma_f32_16x16x32_bf16 v[96:99], v[156:159], v[194:197], v[96:99]
	v_mfma_f32_16x16x32_bf16 v[100:103], v[148:151], v[194:197], v[100:103]
	v_mfma_f32_16x16x32_bf16 v[100:103], v[144:147], v[190:193], v[100:103]
	v_mfma_f32_16x16x32_bf16 v[104:107], v[136:139], v[190:193], v[104:107]
	v_mfma_f32_16x16x32_bf16 v[104:107], v[140:143], v[194:197], v[104:107]
	v_mfma_f32_16x16x32_bf16 v[108:111], v[132:135], v[194:197], v[108:111]
	v_mfma_f32_16x16x32_bf16 v[108:111], v[128:131], v[190:193], v[108:111]
	v_mfma_f32_16x16x32_bf16 v[92:95], v[128:131], v[198:201], v[92:95]
	v_mfma_f32_16x16x32_bf16 v[92:95], v[132:135], v[208:211], v[92:95]
	v_mfma_f32_16x16x32_bf16 v[88:91], v[140:143], v[208:211], v[88:91]
	v_mfma_f32_16x16x32_bf16 v[88:91], v[136:139], v[198:201], v[88:91]
	v_mfma_f32_16x16x32_bf16 v[84:87], v[144:147], v[198:201], v[84:87]
	v_mfma_f32_16x16x32_bf16 v[84:87], v[148:151], v[208:211], v[84:87]
	v_mfma_f32_16x16x32_bf16 v[80:83], v[156:159], v[208:211], v[80:83]
	v_mfma_f32_16x16x32_bf16 v[80:83], v[152:155], v[198:201], v[80:83]
	v_mfma_f32_16x16x32_bf16 v[64:67], v[152:155], v[212:215], v[64:67]
	v_mfma_f32_16x16x32_bf16 v[64:67], v[156:159], v[228:231], v[64:67]
	v_mfma_f32_16x16x32_bf16 v[68:71], v[148:151], v[228:231], v[68:71]
	v_mfma_f32_16x16x32_bf16 v[68:71], v[144:147], v[212:215], v[68:71]
	v_mfma_f32_16x16x32_bf16 v[72:75], v[136:139], v[212:215], v[72:75]
	v_mfma_f32_16x16x32_bf16 v[72:75], v[140:143], v[228:231], v[72:75]
	v_mfma_f32_16x16x32_bf16 v[76:79], v[132:135], v[228:231], v[76:79]
	v_mfma_f32_16x16x32_bf16 v[76:79], v[128:131], v[212:215], v[76:79]
	s_barrier
	s_add_i32 s30, s36, s35
	s_mov_b32 m0, s30
	ds_read_b128 v[182:185], v206 offset:49152
	ds_read_b128 v[186:189], v206 offset:50176
	ds_read_b128 v[190:193], v206 offset:51200
	ds_read_b128 v[194:197], v206 offset:52224
	ds_read_b128 v[198:201], v206 offset:53248
	ds_read_b128 v[208:211], v206 offset:54272
	ds_read_b128 v[212:215], v206 offset:55296
	ds_read_b128 v[228:231], v206 offset:56320
	global_load_lds_dwordx4 v168, s[98:99]
	s_add_i32 m0, s30, 0x2000
	s_add_u32 s26, s26, 0x40080
	s_addc_u32 s27, s27, 0
	s_add_i32 s30, s37, s35
	global_load_lds_dwordx4 v160, s[98:99]
	s_mov_b32 m0, s30
	s_nop 0
	global_load_lds_dwordx4 v168, s[26:27]
	s_add_i32 m0, s30, 0x2000
	s_nop 0
	global_load_lds_dwordx4 v160, s[26:27]
	s_mov_b32 m0, s47
	s_nop 0
	global_load_lds_dwordx4 v164, s[100:101]
	s_mov_b32 m0, s48
	s_nop 0
	global_load_lds_dwordx4 v162, s[100:101]
	s_waitcnt vmcnt(8)
	s_waitcnt lgkmcnt(0)
	s_barrier
	v_mfma_f32_16x16x32_bf16 v[60:63], v[128:131], v[182:185], v[60:63]
	v_mfma_f32_16x16x32_bf16 v[60:63], v[132:135], v[186:189], v[60:63]
	v_mfma_f32_16x16x32_bf16 v[56:59], v[140:143], v[186:189], v[56:59]
	v_mfma_f32_16x16x32_bf16 v[56:59], v[136:139], v[182:185], v[56:59]
	v_mfma_f32_16x16x32_bf16 v[52:55], v[144:147], v[182:185], v[52:55]
	v_mfma_f32_16x16x32_bf16 v[52:55], v[148:151], v[186:189], v[52:55]
	v_mfma_f32_16x16x32_bf16 v[48:51], v[156:159], v[186:189], v[48:51]
	v_mfma_f32_16x16x32_bf16 v[48:51], v[152:155], v[182:185], v[48:51]
	v_mfma_f32_16x16x32_bf16 v[32:35], v[152:155], v[190:193], v[32:35]
	v_mfma_f32_16x16x32_bf16 v[32:35], v[156:159], v[194:197], v[32:35]
	v_mfma_f32_16x16x32_bf16 v[36:39], v[148:151], v[194:197], v[36:39]
	v_mfma_f32_16x16x32_bf16 v[36:39], v[144:147], v[190:193], v[36:39]
	v_mfma_f32_16x16x32_bf16 v[40:43], v[136:139], v[190:193], v[40:43]
	v_mfma_f32_16x16x32_bf16 v[40:43], v[140:143], v[194:197], v[40:43]
	v_mfma_f32_16x16x32_bf16 v[44:47], v[132:135], v[194:197], v[44:47]
	v_mfma_f32_16x16x32_bf16 v[44:47], v[128:131], v[190:193], v[44:47]
	v_mfma_f32_16x16x32_bf16 v[28:31], v[128:131], v[198:201], v[28:31]
	v_mfma_f32_16x16x32_bf16 v[28:31], v[132:135], v[208:211], v[28:31]
	v_mfma_f32_16x16x32_bf16 v[24:27], v[140:143], v[208:211], v[24:27]
	v_mfma_f32_16x16x32_bf16 v[24:27], v[136:139], v[198:201], v[24:27]
	v_mfma_f32_16x16x32_bf16 v[20:23], v[144:147], v[198:201], v[20:23]
	v_mfma_f32_16x16x32_bf16 v[20:23], v[148:151], v[208:211], v[20:23]
	v_mfma_f32_16x16x32_bf16 v[16:19], v[156:159], v[208:211], v[16:19]
	v_mfma_f32_16x16x32_bf16 v[16:19], v[152:155], v[198:201], v[16:19]
	v_mfma_f32_16x16x32_bf16 v[0:3], v[152:155], v[212:215], v[0:3]
	v_mfma_f32_16x16x32_bf16 v[0:3], v[156:159], v[228:231], v[0:3]
	v_mfma_f32_16x16x32_bf16 v[4:7], v[148:151], v[228:231], v[4:7]
	v_mfma_f32_16x16x32_bf16 v[4:7], v[144:147], v[212:215], v[4:7]
	v_mfma_f32_16x16x32_bf16 v[8:11], v[136:139], v[212:215], v[8:11]
	v_mfma_f32_16x16x32_bf16 v[8:11], v[140:143], v[228:231], v[8:11]
	v_mfma_f32_16x16x32_bf16 v[12:15], v[132:135], v[228:231], v[12:15]
	v_mfma_f32_16x16x32_bf16 v[12:15], v[128:131], v[212:215], v[12:15]
	s_barrier
	s_add_i32 s55, s55, 2
	s_add_u32 s22, s22, 0x100
	s_addc_u32 s23, s23, 0
	s_add_u32 s53, s53, 0x100
	s_addc_u32 s54, s54, 0
	s_cmp_gt_u32 s55, 13
	s_cbranch_scc0 .LBB0_776
	s_and_b64 vcc, exec, s[10:11]
	s_cbranch_vccz .LBB0_779
	s_barrier

.LBB0_890:
	s_add_u32 s18, s0, 0xfffc0080
	s_addc_u32 s19, s1, -1
	s_add_i32 s36, 0, 0x10000
	s_cmp_eq_u32 s50, 12
	s_cselect_b32 s23, s13, s19
	s_cselect_b32 s22, s46, s18
	s_cselect_b32 s19, s11, s49
	s_cselect_b32 s18, s47, s48
	s_add_i32 s51, 0, 0x14000
	v_add_u32_e32 v140, s36, v193
	v_add_u32_e32 v180, s51, v193
	ds_read_b128 v[128:131], v140
	ds_read_b128 v[132:135], v140 offset:1024
	ds_read_b128 v[136:139], v140 offset:2048
	ds_read_b128 v[140:143], v140 offset:3072
	ds_read_b128 v[144:147], v180
	ds_read_b128 v[148:151], v180 offset:1024
	ds_read_b128 v[164:167], v180 offset:2048
	ds_read_b128 v[180:183], v180 offset:3072
	s_add_i32 m0, s30, 0xc000
	ds_read_b128 v[184:187], v198
	ds_read_b128 v[188:191], v198 offset:1024
	ds_read_b128 v[200:203], v198 offset:2048
	ds_read_b128 v[204:207], v198 offset:3072
	ds_read_b128 v[208:211], v198 offset:4096
	ds_read_b128 v[212:215], v198 offset:5120
	ds_read_b128 v[228:231], v198 offset:6144
	ds_read_b128 v[232:235], v198 offset:7168
	global_load_lds_dwordx4 v160, s[0:1]
	s_add_i32 m0, s30, 0xe000
	s_nop 0
	global_load_lds_dwordx4 v162, s[0:1]
	s_waitcnt vmcnt(8)
	s_waitcnt lgkmcnt(0)
	s_barrier
	v_mfma_f32_16x16x32_bf16 v[124:127], v[128:131], v[184:187], v[124:127]
	v_mfma_f32_16x16x32_bf16 v[124:127], v[132:135], v[188:191], v[124:127]
	v_mfma_f32_16x16x32_bf16 v[120:123], v[140:143], v[188:191], v[120:123]
	v_mfma_f32_16x16x32_bf16 v[120:123], v[136:139], v[184:187], v[120:123]
	v_mfma_f32_16x16x32_bf16 v[116:119], v[144:147], v[184:187], v[116:119]
	v_mfma_f32_16x16x32_bf16 v[116:119], v[148:151], v[188:191], v[116:119]
	v_mfma_f32_16x16x32_bf16 v[112:115], v[180:183], v[188:191], v[112:115]
	v_mfma_f32_16x16x32_bf16 v[112:115], v[164:167], v[184:187], v[112:115]
	v_mfma_f32_16x16x32_bf16 v[96:99], v[164:167], v[200:203], v[96:99]
	v_mfma_f32_16x16x32_bf16 v[96:99], v[180:183], v[204:207], v[96:99]
	v_mfma_f32_16x16x32_bf16 v[100:103], v[148:151], v[204:207], v[100:103]
	v_mfma_f32_16x16x32_bf16 v[100:103], v[144:147], v[200:203], v[100:103]
	v_mfma_f32_16x16x32_bf16 v[104:107], v[136:139], v[200:203], v[104:107]
	v_mfma_f32_16x16x32_bf16 v[104:107], v[140:143], v[204:207], v[104:107]
	v_mfma_f32_16x16x32_bf16 v[108:111], v[132:135], v[204:207], v[108:111]
	v_mfma_f32_16x16x32_bf16 v[108:111], v[128:131], v[200:203], v[108:111]
	v_mfma_f32_16x16x32_bf16 v[92:95], v[128:131], v[208:211], v[92:95]
	v_mfma_f32_16x16x32_bf16 v[92:95], v[132:135], v[212:215], v[92:95]
	v_mfma_f32_16x16x32_bf16 v[88:91], v[140:143], v[212:215], v[88:91]
	v_mfma_f32_16x16x32_bf16 v[88:91], v[136:139], v[208:211], v[88:91]
	v_mfma_f32_16x16x32_bf16 v[84:87], v[144:147], v[208:211], v[84:87]
	v_mfma_f32_16x16x32_bf16 v[84:87], v[148:151], v[212:215], v[84:87]
	v_mfma_f32_16x16x32_bf16 v[80:83], v[180:183], v[212:215], v[80:83]
	v_mfma_f32_16x16x32_bf16 v[80:83], v[164:167], v[208:211], v[80:83]
	v_mfma_f32_16x16x32_bf16 v[64:67], v[164:167], v[228:231], v[64:67]
	v_mfma_f32_16x16x32_bf16 v[64:67], v[180:183], v[232:235], v[64:67]
	v_mfma_f32_16x16x32_bf16 v[68:71], v[148:151], v[232:235], v[68:71]
	v_mfma_f32_16x16x32_bf16 v[68:71], v[144:147], v[228:231], v[68:71]
	v_mfma_f32_16x16x32_bf16 v[72:75], v[136:139], v[228:231], v[72:75]
	v_mfma_f32_16x16x32_bf16 v[72:75], v[140:143], v[232:235], v[72:75]
	v_mfma_f32_16x16x32_bf16 v[76:79], v[132:135], v[232:235], v[76:79]
	v_mfma_f32_16x16x32_bf16 v[76:79], v[128:131], v[228:231], v[76:79]
	s_barrier
	s_add_i32 s36, s36, s27
	s_add_u32 s98, s18, s20
	s_addc_u32 s99, s19, s21
	s_mov_b32 m0, s36
	ds_read_b128 v[184:187], v198 offset:16384
	ds_read_b128 v[188:191], v198 offset:17408
	ds_read_b128 v[200:203], v198 offset:18432
	ds_read_b128 v[204:207], v198 offset:19456
	ds_read_b128 v[208:211], v198 offset:20480
	ds_read_b128 v[212:215], v198 offset:21504
	ds_read_b128 v[228:231], v198 offset:22528
	ds_read_b128 v[232:235], v198 offset:23552
	global_load_lds_dwordx4 v168, s[18:19]
	s_add_i32 m0, s36, 0x2000
	s_add_u32 s36, s18, 0x40000
	s_addc_u32 s37, s19, 0
	s_add_i32 s51, s51, s27
	global_load_lds_dwordx4 v152, s[18:19]
	s_mov_b32 m0, s51
	s_nop 0
	global_load_lds_dwordx4 v168, s[36:37]
	s_add_i32 m0, s51, 0x2000
	s_nop 0
	global_load_lds_dwordx4 v152, s[36:37]
	s_add_u32 s100, s22, s20
	s_addc_u32 s101, s23, s21
	s_mov_b32 m0, s30
	s_nop 0
	global_load_lds_dwordx4 v156, s[22:23]
	s_mov_b32 m0, s31
	s_nop 0
	global_load_lds_dwordx4 v154, s[22:23]
	s_waitcnt vmcnt(8)
	s_waitcnt lgkmcnt(0)
	s_barrier
	v_mfma_f32_16x16x32_bf16 v[60:63], v[128:131], v[184:187], v[60:63]
	v_mfma_f32_16x16x32_bf16 v[60:63], v[132:135], v[188:191], v[60:63]
	v_mfma_f32_16x16x32_bf16 v[56:59], v[140:143], v[188:191], v[56:59]
	v_mfma_f32_16x16x32_bf16 v[56:59], v[136:139], v[184:187], v[56:59]
	v_mfma_f32_16x16x32_bf16 v[52:55], v[144:147], v[184:187], v[52:55]
	v_mfma_f32_16x16x32_bf16 v[52:55], v[148:151], v[188:191], v[52:55]
	v_mfma_f32_16x16x32_bf16 v[48:51], v[180:183], v[188:191], v[48:51]
	v_mfma_f32_16x16x32_bf16 v[48:51], v[164:167], v[184:187], v[48:51]
	v_mfma_f32_16x16x32_bf16 v[32:35], v[164:167], v[200:203], v[32:35]
	v_mfma_f32_16x16x32_bf16 v[32:35], v[180:183], v[204:207], v[32:35]
	v_mfma_f32_16x16x32_bf16 v[36:39], v[148:151], v[204:207], v[36:39]
	v_mfma_f32_16x16x32_bf16 v[36:39], v[144:147], v[200:203], v[36:39]
	v_mfma_f32_16x16x32_bf16 v[40:43], v[136:139], v[200:203], v[40:43]
	v_mfma_f32_16x16x32_bf16 v[40:43], v[140:143], v[204:207], v[40:43]
	v_mfma_f32_16x16x32_bf16 v[44:47], v[132:135], v[204:207], v[44:47]
	v_mfma_f32_16x16x32_bf16 v[44:47], v[128:131], v[200:203], v[44:47]
	v_mfma_f32_16x16x32_bf16 v[28:31], v[128:131], v[208:211], v[28:31]
	v_mfma_f32_16x16x32_bf16 v[28:31], v[132:135], v[212:215], v[28:31]
	v_mfma_f32_16x16x32_bf16 v[24:27], v[140:143], v[212:215], v[24:27]
	v_mfma_f32_16x16x32_bf16 v[24:27], v[136:139], v[208:211], v[24:27]
	v_mfma_f32_16x16x32_bf16 v[20:23], v[144:147], v[208:211], v[20:23]
	v_mfma_f32_16x16x32_bf16 v[20:23], v[148:151], v[212:215], v[20:23]
	v_mfma_f32_16x16x32_bf16 v[16:19], v[180:183], v[212:215], v[16:19]
	v_mfma_f32_16x16x32_bf16 v[16:19], v[164:167], v[208:211], v[16:19]
	v_mfma_f32_16x16x32_bf16 v[0:3], v[164:167], v[228:231], v[0:3]
	v_mfma_f32_16x16x32_bf16 v[0:3], v[180:183], v[232:235], v[0:3]
	v_mfma_f32_16x16x32_bf16 v[4:7], v[148:151], v[232:235], v[4:7]
	v_mfma_f32_16x16x32_bf16 v[4:7], v[144:147], v[228:231], v[4:7]
	v_mfma_f32_16x16x32_bf16 v[8:11], v[136:139], v[228:231], v[8:11]
	v_mfma_f32_16x16x32_bf16 v[8:11], v[140:143], v[232:235], v[8:11]
	v_mfma_f32_16x16x32_bf16 v[12:15], v[132:135], v[232:235], v[12:15]
	v_mfma_f32_16x16x32_bf16 v[12:15], v[128:131], v[228:231], v[12:15]
	s_barrier
	s_add_i32 s36, 0, 0x18000
	s_add_i32 s37, 0, 0x1c000
	v_add_u32_e32 v140, s36, v193
	v_add_u32_e32 v180, s37, v193
	ds_read_b128 v[128:131], v140
	ds_read_b128 v[132:135], v140 offset:1024
	ds_read_b128 v[136:139], v140 offset:2048
	ds_read_b128 v[140:143], v140 offset:3072
	ds_read_b128 v[144:147], v180
	ds_read_b128 v[148:151], v180 offset:1024
	ds_read_b128 v[164:167], v180 offset:2048
	ds_read_b128 v[180:183], v180 offset:3072
	s_add_u32 s22, s22, 0x40000
	s_addc_u32 s23, s23, 0
	s_mov_b32 m0, s34
	ds_read_b128 v[184:187], v198 offset:32768
	ds_read_b128 v[188:191], v198 offset:33792
	ds_read_b128 v[200:203], v198 offset:34816
	ds_read_b128 v[204:207], v198 offset:35840
	ds_read_b128 v[208:211], v198 offset:36864
	ds_read_b128 v[212:215], v198 offset:37888
	ds_read_b128 v[228:231], v198 offset:38912
	ds_read_b128 v[232:235], v198 offset:39936
	global_load_lds_dwordx4 v156, s[22:23]
	s_mov_b32 m0, s35
	s_nop 0
	global_load_lds_dwordx4 v154, s[22:23]
	s_waitcnt vmcnt(8)
	s_waitcnt lgkmcnt(0)
	s_barrier
	v_mfma_f32_16x16x32_bf16 v[124:127], v[128:131], v[184:187], v[124:127]
	v_mfma_f32_16x16x32_bf16 v[124:127], v[132:135], v[188:191], v[124:127]
	v_mfma_f32_16x16x32_bf16 v[120:123], v[140:143], v[188:191], v[120:123]
	v_mfma_f32_16x16x32_bf16 v[120:123], v[136:139], v[184:187], v[120:123]
	v_mfma_f32_16x16x32_bf16 v[116:119], v[144:147], v[184:187], v[116:119]
	v_mfma_f32_16x16x32_bf16 v[116:119], v[148:151], v[188:191], v[116:119]
	v_mfma_f32_16x16x32_bf16 v[112:115], v[180:183], v[188:191], v[112:115]
	v_mfma_f32_16x16x32_bf16 v[112:115], v[164:167], v[184:187], v[112:115]
	v_mfma_f32_16x16x32_bf16 v[96:99], v[164:167], v[200:203], v[96:99]
	v_mfma_f32_16x16x32_bf16 v[96:99], v[180:183], v[204:207], v[96:99]
	v_mfma_f32_16x16x32_bf16 v[100:103], v[148:151], v[204:207], v[100:103]
	v_mfma_f32_16x16x32_bf16 v[100:103], v[144:147], v[200:203], v[100:103]
	v_mfma_f32_16x16x32_bf16 v[104:107], v[136:139], v[200:203], v[104:107]
	v_mfma_f32_16x16x32_bf16 v[104:107], v[140:143], v[204:207], v[104:107]
	v_mfma_f32_16x16x32_bf16 v[108:111], v[132:135], v[204:207], v[108:111]
	v_mfma_f32_16x16x32_bf16 v[108:111], v[128:131], v[200:203], v[108:111]
	v_mfma_f32_16x16x32_bf16 v[92:95], v[128:131], v[208:211], v[92:95]
	v_mfma_f32_16x16x32_bf16 v[92:95], v[132:135], v[212:215], v[92:95]
	v_mfma_f32_16x16x32_bf16 v[88:91], v[140:143], v[212:215], v[88:91]
	v_mfma_f32_16x16x32_bf16 v[88:91], v[136:139], v[208:211], v[88:91]
	v_mfma_f32_16x16x32_bf16 v[84:87], v[144:147], v[208:211], v[84:87]
	v_mfma_f32_16x16x32_bf16 v[84:87], v[148:151], v[212:215], v[84:87]
	v_mfma_f32_16x16x32_bf16 v[80:83], v[180:183], v[212:215], v[80:83]
	v_mfma_f32_16x16x32_bf16 v[80:83], v[164:167], v[208:211], v[80:83]
	v_mfma_f32_16x16x32_bf16 v[64:67], v[164:167], v[228:231], v[64:67]
	v_mfma_f32_16x16x32_bf16 v[64:67], v[180:183], v[232:235], v[64:67]
	v_mfma_f32_16x16x32_bf16 v[68:71], v[148:151], v[232:235], v[68:71]
	v_mfma_f32_16x16x32_bf16 v[68:71], v[144:147], v[228:231], v[68:71]
	v_mfma_f32_16x16x32_bf16 v[72:75], v[136:139], v[228:231], v[72:75]
	v_mfma_f32_16x16x32_bf16 v[72:75], v[140:143], v[232:235], v[72:75]
	v_mfma_f32_16x16x32_bf16 v[76:79], v[132:135], v[232:235], v[76:79]
	v_mfma_f32_16x16x32_bf16 v[76:79], v[128:131], v[228:231], v[76:79]
	s_barrier
	s_add_i32 s22, s36, s27
	s_mov_b32 m0, s22
	ds_read_b128 v[184:187], v198 offset:49152
	ds_read_b128 v[188:191], v198 offset:50176
	ds_read_b128 v[200:203], v198 offset:51200
	ds_read_b128 v[204:207], v198 offset:52224
	ds_read_b128 v[208:211], v198 offset:53248
	ds_read_b128 v[212:215], v198 offset:54272
	ds_read_b128 v[228:231], v198 offset:55296
	ds_read_b128 v[232:235], v198 offset:56320
	global_load_lds_dwordx4 v168, s[98:99]
	s_add_i32 m0, s22, 0x2000
	s_add_u32 s18, s18, 0x40080
	s_addc_u32 s19, s19, 0
	s_add_i32 s22, s37, s27
	global_load_lds_dwordx4 v152, s[98:99]
	s_mov_b32 m0, s22
	s_nop 0
	global_load_lds_dwordx4 v168, s[18:19]
	s_add_i32 m0, s22, 0x2000
	s_nop 0
	global_load_lds_dwordx4 v152, s[18:19]
	s_mov_b32 m0, s24
	s_nop 0
	global_load_lds_dwordx4 v156, s[100:101]
	s_mov_b32 m0, s42
	s_nop 0
	global_load_lds_dwordx4 v154, s[100:101]
	s_waitcnt vmcnt(8)
	s_waitcnt lgkmcnt(0)
	s_barrier
	v_mfma_f32_16x16x32_bf16 v[60:63], v[128:131], v[184:187], v[60:63]
	v_mfma_f32_16x16x32_bf16 v[60:63], v[132:135], v[188:191], v[60:63]
	v_mfma_f32_16x16x32_bf16 v[56:59], v[140:143], v[188:191], v[56:59]
	v_mfma_f32_16x16x32_bf16 v[56:59], v[136:139], v[184:187], v[56:59]
	v_mfma_f32_16x16x32_bf16 v[52:55], v[144:147], v[184:187], v[52:55]
	v_mfma_f32_16x16x32_bf16 v[52:55], v[148:151], v[188:191], v[52:55]
	v_mfma_f32_16x16x32_bf16 v[48:51], v[180:183], v[188:191], v[48:51]
	v_mfma_f32_16x16x32_bf16 v[48:51], v[164:167], v[184:187], v[48:51]
	v_mfma_f32_16x16x32_bf16 v[32:35], v[164:167], v[200:203], v[32:35]
	v_mfma_f32_16x16x32_bf16 v[32:35], v[180:183], v[204:207], v[32:35]
	v_mfma_f32_16x16x32_bf16 v[36:39], v[148:151], v[204:207], v[36:39]
	v_mfma_f32_16x16x32_bf16 v[36:39], v[144:147], v[200:203], v[36:39]
	v_mfma_f32_16x16x32_bf16 v[40:43], v[136:139], v[200:203], v[40:43]
	v_mfma_f32_16x16x32_bf16 v[40:43], v[140:143], v[204:207], v[40:43]
	v_mfma_f32_16x16x32_bf16 v[44:47], v[132:135], v[204:207], v[44:47]
	v_mfma_f32_16x16x32_bf16 v[44:47], v[128:131], v[200:203], v[44:47]
	v_mfma_f32_16x16x32_bf16 v[28:31], v[128:131], v[208:211], v[28:31]
	v_mfma_f32_16x16x32_bf16 v[28:31], v[132:135], v[212:215], v[28:31]
	v_mfma_f32_16x16x32_bf16 v[24:27], v[140:143], v[212:215], v[24:27]
	v_mfma_f32_16x16x32_bf16 v[24:27], v[136:139], v[208:211], v[24:27]
	v_mfma_f32_16x16x32_bf16 v[20:23], v[144:147], v[208:211], v[20:23]
	v_mfma_f32_16x16x32_bf16 v[20:23], v[148:151], v[212:215], v[20:23]
	v_mfma_f32_16x16x32_bf16 v[16:19], v[180:183], v[212:215], v[16:19]
	v_mfma_f32_16x16x32_bf16 v[16:19], v[164:167], v[208:211], v[16:19]
	v_mfma_f32_16x16x32_bf16 v[0:3], v[164:167], v[228:231], v[0:3]
	v_mfma_f32_16x16x32_bf16 v[0:3], v[180:183], v[232:235], v[0:3]
	v_mfma_f32_16x16x32_bf16 v[4:7], v[148:151], v[232:235], v[4:7]
	v_mfma_f32_16x16x32_bf16 v[4:7], v[144:147], v[228:231], v[4:7]
	v_mfma_f32_16x16x32_bf16 v[8:11], v[136:139], v[228:231], v[8:11]
	v_mfma_f32_16x16x32_bf16 v[8:11], v[140:143], v[232:235], v[8:11]
	v_mfma_f32_16x16x32_bf16 v[12:15], v[132:135], v[232:235], v[12:15]
	v_mfma_f32_16x16x32_bf16 v[12:15], v[128:131], v[228:231], v[12:15]
	s_barrier
	s_add_i32 s50, s50, 2
	s_add_u32 s0, s0, 0x100
	s_addc_u32 s1, s1, 0
	s_add_u32 s48, s48, 0x100
	s_addc_u32 s49, s49, 0
	s_cmp_gt_u32 s50, 13
	s_cbranch_scc0 .LBB0_890
	s_and_b64 vcc, exec, s[8:9]
	s_cbranch_vccz .LBB0_893
	s_barrier

.LBB0_986:
	s_add_u32 s34, s8, 0xfff00080
	s_addc_u32 s35, s9, -1
	s_add_i32 s36, 0, 0x10000
	s_cmp_eq_u32 s57, 60
	s_cselect_b32 s41, s23, s35
	s_cselect_b32 s40, s53, s34
	s_cselect_b32 s35, s19, s56
	s_cselect_b32 s34, s54, s55
	s_add_i32 s58, 0, 0x14000
	v_add_u32_e32 v140, s36, v228
	v_add_u32_e32 v156, s58, v228
	ds_read_b128 v[128:131], v140
	ds_read_b128 v[132:135], v140 offset:1024
	ds_read_b128 v[136:139], v140 offset:2048
	ds_read_b128 v[140:143], v140 offset:3072
	ds_read_b128 v[144:147], v156
	ds_read_b128 v[148:151], v156 offset:1024
	ds_read_b128 v[152:155], v156 offset:2048
	ds_read_b128 v[156:159], v156 offset:3072
	s_add_i32 m0, s44, 0xc000
	ds_read_b128 v[160:163], v230
	ds_read_b128 v[164:167], v230 offset:1024
	ds_read_b128 v[190:193], v230 offset:2048
	ds_read_b128 v[194:197], v230 offset:3072
	ds_read_b128 v[198:201], v230 offset:4096
	ds_read_b128 v[202:205], v230 offset:5120
	ds_read_b128 v[206:209], v230 offset:6144
	ds_read_b128 v[210:213], v230 offset:7168
	global_load_lds_dwordx4 v186, s[8:9]
	s_add_i32 m0, s44, 0xe000
	s_nop 0
	global_load_lds_dwordx4 v188, s[8:9]
	s_waitcnt vmcnt(8)
	s_waitcnt lgkmcnt(0)
	s_barrier
	v_mfma_f32_16x16x32_bf16 v[124:127], v[128:131], v[160:163], v[124:127]
	v_mfma_f32_16x16x32_bf16 v[124:127], v[132:135], v[164:167], v[124:127]
	v_mfma_f32_16x16x32_bf16 v[120:123], v[140:143], v[164:167], v[120:123]
	v_mfma_f32_16x16x32_bf16 v[120:123], v[136:139], v[160:163], v[120:123]
	v_mfma_f32_16x16x32_bf16 v[116:119], v[144:147], v[160:163], v[116:119]
	v_mfma_f32_16x16x32_bf16 v[116:119], v[148:151], v[164:167], v[116:119]
	v_mfma_f32_16x16x32_bf16 v[112:115], v[156:159], v[164:167], v[112:115]
	v_mfma_f32_16x16x32_bf16 v[112:115], v[152:155], v[160:163], v[112:115]
	v_mfma_f32_16x16x32_bf16 v[96:99], v[152:155], v[190:193], v[96:99]
	v_mfma_f32_16x16x32_bf16 v[96:99], v[156:159], v[194:197], v[96:99]
	v_mfma_f32_16x16x32_bf16 v[100:103], v[148:151], v[194:197], v[100:103]
	v_mfma_f32_16x16x32_bf16 v[100:103], v[144:147], v[190:193], v[100:103]
	v_mfma_f32_16x16x32_bf16 v[104:107], v[136:139], v[190:193], v[104:107]
	v_mfma_f32_16x16x32_bf16 v[104:107], v[140:143], v[194:197], v[104:107]
	v_mfma_f32_16x16x32_bf16 v[108:111], v[132:135], v[194:197], v[108:111]
	v_mfma_f32_16x16x32_bf16 v[108:111], v[128:131], v[190:193], v[108:111]
	v_mfma_f32_16x16x32_bf16 v[92:95], v[128:131], v[198:201], v[92:95]
	v_mfma_f32_16x16x32_bf16 v[92:95], v[132:135], v[202:205], v[92:95]
	v_mfma_f32_16x16x32_bf16 v[88:91], v[140:143], v[202:205], v[88:91]
	v_mfma_f32_16x16x32_bf16 v[88:91], v[136:139], v[198:201], v[88:91]
	v_mfma_f32_16x16x32_bf16 v[84:87], v[144:147], v[198:201], v[84:87]
	v_mfma_f32_16x16x32_bf16 v[84:87], v[148:151], v[202:205], v[84:87]
	v_mfma_f32_16x16x32_bf16 v[80:83], v[156:159], v[202:205], v[80:83]
	v_mfma_f32_16x16x32_bf16 v[80:83], v[152:155], v[198:201], v[80:83]
	v_mfma_f32_16x16x32_bf16 v[64:67], v[152:155], v[206:209], v[64:67]
	v_mfma_f32_16x16x32_bf16 v[64:67], v[156:159], v[210:213], v[64:67]
	v_mfma_f32_16x16x32_bf16 v[68:71], v[148:151], v[210:213], v[68:71]
	v_mfma_f32_16x16x32_bf16 v[68:71], v[144:147], v[206:209], v[68:71]
	v_mfma_f32_16x16x32_bf16 v[72:75], v[136:139], v[206:209], v[72:75]
	v_mfma_f32_16x16x32_bf16 v[72:75], v[140:143], v[210:213], v[72:75]
	v_mfma_f32_16x16x32_bf16 v[76:79], v[132:135], v[210:213], v[76:79]
	v_mfma_f32_16x16x32_bf16 v[76:79], v[128:131], v[206:209], v[76:79]
	s_barrier
	s_add_i32 s36, s36, s43
	s_add_u32 s98, s34, s20
	s_addc_u32 s99, s35, s21
	s_mov_b32 m0, s36
	ds_read_b128 v[160:163], v230 offset:16384
	ds_read_b128 v[164:167], v230 offset:17408
	ds_read_b128 v[190:193], v230 offset:18432
	ds_read_b128 v[194:197], v230 offset:19456
	ds_read_b128 v[198:201], v230 offset:20480
	ds_read_b128 v[202:205], v230 offset:21504
	ds_read_b128 v[206:209], v230 offset:22528
	ds_read_b128 v[210:213], v230 offset:23552
	global_load_lds_dwordx4 v168, s[34:35]
	s_add_i32 m0, s36, 0x2000
	s_add_u32 s36, s34, 0x100000
	s_addc_u32 s37, s35, 0
	s_add_i32 s58, s58, s43
	global_load_lds_dwordx4 v180, s[34:35]
	s_mov_b32 m0, s58
	s_nop 0
	global_load_lds_dwordx4 v168, s[36:37]
	s_add_i32 m0, s58, 0x2000
	s_nop 0
	global_load_lds_dwordx4 v180, s[36:37]
	s_add_u32 s100, s40, s20
	s_addc_u32 s101, s41, s21
	s_mov_b32 m0, s44
	s_nop 0
	global_load_lds_dwordx4 v184, s[40:41]
	s_mov_b32 m0, s45
	s_nop 0
	global_load_lds_dwordx4 v182, s[40:41]
	s_waitcnt vmcnt(8)
	s_waitcnt lgkmcnt(0)
	s_barrier
	v_mfma_f32_16x16x32_bf16 v[60:63], v[128:131], v[160:163], v[60:63]
	v_mfma_f32_16x16x32_bf16 v[60:63], v[132:135], v[164:167], v[60:63]
	v_mfma_f32_16x16x32_bf16 v[56:59], v[140:143], v[164:167], v[56:59]
	v_mfma_f32_16x16x32_bf16 v[56:59], v[136:139], v[160:163], v[56:59]
	v_mfma_f32_16x16x32_bf16 v[52:55], v[144:147], v[160:163], v[52:55]
	v_mfma_f32_16x16x32_bf16 v[52:55], v[148:151], v[164:167], v[52:55]
	v_mfma_f32_16x16x32_bf16 v[48:51], v[156:159], v[164:167], v[48:51]
	v_mfma_f32_16x16x32_bf16 v[48:51], v[152:155], v[160:163], v[48:51]
	v_mfma_f32_16x16x32_bf16 v[32:35], v[152:155], v[190:193], v[32:35]
	v_mfma_f32_16x16x32_bf16 v[32:35], v[156:159], v[194:197], v[32:35]
	v_mfma_f32_16x16x32_bf16 v[36:39], v[148:151], v[194:197], v[36:39]
	v_mfma_f32_16x16x32_bf16 v[36:39], v[144:147], v[190:193], v[36:39]
	v_mfma_f32_16x16x32_bf16 v[40:43], v[136:139], v[190:193], v[40:43]
	v_mfma_f32_16x16x32_bf16 v[40:43], v[140:143], v[194:197], v[40:43]
	v_mfma_f32_16x16x32_bf16 v[44:47], v[132:135], v[194:197], v[44:47]
	v_mfma_f32_16x16x32_bf16 v[44:47], v[128:131], v[190:193], v[44:47]
	v_mfma_f32_16x16x32_bf16 v[28:31], v[128:131], v[198:201], v[28:31]
	v_mfma_f32_16x16x32_bf16 v[28:31], v[132:135], v[202:205], v[28:31]
	v_mfma_f32_16x16x32_bf16 v[24:27], v[140:143], v[202:205], v[24:27]
	v_mfma_f32_16x16x32_bf16 v[24:27], v[136:139], v[198:201], v[24:27]
	v_mfma_f32_16x16x32_bf16 v[20:23], v[144:147], v[198:201], v[20:23]
	v_mfma_f32_16x16x32_bf16 v[20:23], v[148:151], v[202:205], v[20:23]
	v_mfma_f32_16x16x32_bf16 v[16:19], v[156:159], v[202:205], v[16:19]
	v_mfma_f32_16x16x32_bf16 v[16:19], v[152:155], v[198:201], v[16:19]
	v_mfma_f32_16x16x32_bf16 v[0:3], v[152:155], v[206:209], v[0:3]
	v_mfma_f32_16x16x32_bf16 v[0:3], v[156:159], v[210:213], v[0:3]
	v_mfma_f32_16x16x32_bf16 v[4:7], v[148:151], v[210:213], v[4:7]
	v_mfma_f32_16x16x32_bf16 v[4:7], v[144:147], v[206:209], v[4:7]
	v_mfma_f32_16x16x32_bf16 v[8:11], v[136:139], v[206:209], v[8:11]
	v_mfma_f32_16x16x32_bf16 v[8:11], v[140:143], v[210:213], v[8:11]
	v_mfma_f32_16x16x32_bf16 v[12:15], v[132:135], v[210:213], v[12:15]
	v_mfma_f32_16x16x32_bf16 v[12:15], v[128:131], v[206:209], v[12:15]
	s_barrier
	s_add_i32 s58, 0, 0x18000
	s_add_i32 s59, 0, 0x1c000
	v_add_u32_e32 v140, s58, v228
	v_add_u32_e32 v156, s59, v228
	ds_read_b128 v[128:131], v140
	ds_read_b128 v[132:135], v140 offset:1024
	ds_read_b128 v[136:139], v140 offset:2048
	ds_read_b128 v[140:143], v140 offset:3072
	ds_read_b128 v[144:147], v156
	ds_read_b128 v[148:151], v156 offset:1024
	ds_read_b128 v[152:155], v156 offset:2048
	ds_read_b128 v[156:159], v156 offset:3072
	s_add_u32 s36, s40, 0x100000
	s_addc_u32 s37, s41, 0
	s_mov_b32 m0, s46
	ds_read_b128 v[160:163], v230 offset:32768
	ds_read_b128 v[164:167], v230 offset:33792
	ds_read_b128 v[190:193], v230 offset:34816
	ds_read_b128 v[194:197], v230 offset:35840
	ds_read_b128 v[198:201], v230 offset:36864
	ds_read_b128 v[202:205], v230 offset:37888
	ds_read_b128 v[206:209], v230 offset:38912
	ds_read_b128 v[210:213], v230 offset:39936
	global_load_lds_dwordx4 v184, s[36:37]
	s_mov_b32 m0, s47
	s_nop 0
	global_load_lds_dwordx4 v182, s[36:37]
	s_waitcnt vmcnt(8)
	s_waitcnt lgkmcnt(0)
	s_barrier
	v_mfma_f32_16x16x32_bf16 v[124:127], v[128:131], v[160:163], v[124:127]
	v_mfma_f32_16x16x32_bf16 v[124:127], v[132:135], v[164:167], v[124:127]
	v_mfma_f32_16x16x32_bf16 v[120:123], v[140:143], v[164:167], v[120:123]
	v_mfma_f32_16x16x32_bf16 v[120:123], v[136:139], v[160:163], v[120:123]
	v_mfma_f32_16x16x32_bf16 v[116:119], v[144:147], v[160:163], v[116:119]
	v_mfma_f32_16x16x32_bf16 v[116:119], v[148:151], v[164:167], v[116:119]
	v_mfma_f32_16x16x32_bf16 v[112:115], v[156:159], v[164:167], v[112:115]
	v_mfma_f32_16x16x32_bf16 v[112:115], v[152:155], v[160:163], v[112:115]
	v_mfma_f32_16x16x32_bf16 v[96:99], v[152:155], v[190:193], v[96:99]
	v_mfma_f32_16x16x32_bf16 v[96:99], v[156:159], v[194:197], v[96:99]
	v_mfma_f32_16x16x32_bf16 v[100:103], v[148:151], v[194:197], v[100:103]
	v_mfma_f32_16x16x32_bf16 v[100:103], v[144:147], v[190:193], v[100:103]
	v_mfma_f32_16x16x32_bf16 v[104:107], v[136:139], v[190:193], v[104:107]
	v_mfma_f32_16x16x32_bf16 v[104:107], v[140:143], v[194:197], v[104:107]
	v_mfma_f32_16x16x32_bf16 v[108:111], v[132:135], v[194:197], v[108:111]
	v_mfma_f32_16x16x32_bf16 v[108:111], v[128:131], v[190:193], v[108:111]
	v_mfma_f32_16x16x32_bf16 v[92:95], v[128:131], v[198:201], v[92:95]
	v_mfma_f32_16x16x32_bf16 v[92:95], v[132:135], v[202:205], v[92:95]
	v_mfma_f32_16x16x32_bf16 v[88:91], v[140:143], v[202:205], v[88:91]
	v_mfma_f32_16x16x32_bf16 v[88:91], v[136:139], v[198:201], v[88:91]
	v_mfma_f32_16x16x32_bf16 v[84:87], v[144:147], v[198:201], v[84:87]
	v_mfma_f32_16x16x32_bf16 v[84:87], v[148:151], v[202:205], v[84:87]
	v_mfma_f32_16x16x32_bf16 v[80:83], v[156:159], v[202:205], v[80:83]
	v_mfma_f32_16x16x32_bf16 v[80:83], v[152:155], v[198:201], v[80:83]
	v_mfma_f32_16x16x32_bf16 v[64:67], v[152:155], v[206:209], v[64:67]
	v_mfma_f32_16x16x32_bf16 v[64:67], v[156:159], v[210:213], v[64:67]
	v_mfma_f32_16x16x32_bf16 v[68:71], v[148:151], v[210:213], v[68:71]
	v_mfma_f32_16x16x32_bf16 v[68:71], v[144:147], v[206:209], v[68:71]
	v_mfma_f32_16x16x32_bf16 v[72:75], v[136:139], v[206:209], v[72:75]
	v_mfma_f32_16x16x32_bf16 v[72:75], v[140:143], v[210:213], v[72:75]
	v_mfma_f32_16x16x32_bf16 v[76:79], v[132:135], v[210:213], v[76:79]
	v_mfma_f32_16x16x32_bf16 v[76:79], v[128:131], v[206:209], v[76:79]
	s_barrier
	s_add_i32 s36, s58, s43
	s_mov_b32 m0, s36
	ds_read_b128 v[160:163], v230 offset:49152
	ds_read_b128 v[164:167], v230 offset:50176
	ds_read_b128 v[190:193], v230 offset:51200
	ds_read_b128 v[194:197], v230 offset:52224
	ds_read_b128 v[198:201], v230 offset:53248
	ds_read_b128 v[202:205], v230 offset:54272
	ds_read_b128 v[206:209], v230 offset:55296
	ds_read_b128 v[210:213], v230 offset:56320
	global_load_lds_dwordx4 v168, s[98:99]
	s_add_i32 m0, s36, 0x2000
	s_add_u32 s34, s34, 0x100080
	s_addc_u32 s35, s35, 0
	s_add_i32 s36, s59, s43
	global_load_lds_dwordx4 v180, s[98:99]
	s_mov_b32 m0, s36
	s_nop 0
	global_load_lds_dwordx4 v168, s[34:35]
	s_add_i32 m0, s36, 0x2000
	s_nop 0
	global_load_lds_dwordx4 v180, s[34:35]
	s_mov_b32 m0, s50
	s_nop 0
	global_load_lds_dwordx4 v184, s[100:101]
	s_mov_b32 m0, s51
	s_nop 0
	global_load_lds_dwordx4 v182, s[100:101]
	s_waitcnt vmcnt(8)
	s_waitcnt lgkmcnt(0)
	s_barrier
	v_mfma_f32_16x16x32_bf16 v[60:63], v[128:131], v[160:163], v[60:63]
	v_mfma_f32_16x16x32_bf16 v[60:63], v[132:135], v[164:167], v[60:63]
	v_mfma_f32_16x16x32_bf16 v[56:59], v[140:143], v[164:167], v[56:59]
	v_mfma_f32_16x16x32_bf16 v[56:59], v[136:139], v[160:163], v[56:59]
	v_mfma_f32_16x16x32_bf16 v[52:55], v[144:147], v[160:163], v[52:55]
	v_mfma_f32_16x16x32_bf16 v[52:55], v[148:151], v[164:167], v[52:55]
	v_mfma_f32_16x16x32_bf16 v[48:51], v[156:159], v[164:167], v[48:51]
	v_mfma_f32_16x16x32_bf16 v[48:51], v[152:155], v[160:163], v[48:51]
	v_mfma_f32_16x16x32_bf16 v[32:35], v[152:155], v[190:193], v[32:35]
	v_mfma_f32_16x16x32_bf16 v[32:35], v[156:159], v[194:197], v[32:35]
	v_mfma_f32_16x16x32_bf16 v[36:39], v[148:151], v[194:197], v[36:39]
	v_mfma_f32_16x16x32_bf16 v[36:39], v[144:147], v[190:193], v[36:39]
	v_mfma_f32_16x16x32_bf16 v[40:43], v[136:139], v[190:193], v[40:43]
	v_mfma_f32_16x16x32_bf16 v[40:43], v[140:143], v[194:197], v[40:43]
	v_mfma_f32_16x16x32_bf16 v[44:47], v[132:135], v[194:197], v[44:47]
	v_mfma_f32_16x16x32_bf16 v[44:47], v[128:131], v[190:193], v[44:47]
	v_mfma_f32_16x16x32_bf16 v[28:31], v[128:131], v[198:201], v[28:31]
	v_mfma_f32_16x16x32_bf16 v[28:31], v[132:135], v[202:205], v[28:31]
	v_mfma_f32_16x16x32_bf16 v[24:27], v[140:143], v[202:205], v[24:27]
	v_mfma_f32_16x16x32_bf16 v[24:27], v[136:139], v[198:201], v[24:27]
	v_mfma_f32_16x16x32_bf16 v[20:23], v[144:147], v[198:201], v[20:23]
	v_mfma_f32_16x16x32_bf16 v[20:23], v[148:151], v[202:205], v[20:23]
	v_mfma_f32_16x16x32_bf16 v[16:19], v[156:159], v[202:205], v[16:19]
	v_mfma_f32_16x16x32_bf16 v[16:19], v[152:155], v[198:201], v[16:19]
	v_mfma_f32_16x16x32_bf16 v[0:3], v[152:155], v[206:209], v[0:3]
	v_mfma_f32_16x16x32_bf16 v[0:3], v[156:159], v[210:213], v[0:3]
	v_mfma_f32_16x16x32_bf16 v[4:7], v[148:151], v[210:213], v[4:7]
	v_mfma_f32_16x16x32_bf16 v[4:7], v[144:147], v[206:209], v[4:7]
	v_mfma_f32_16x16x32_bf16 v[8:11], v[136:139], v[206:209], v[8:11]
	v_mfma_f32_16x16x32_bf16 v[8:11], v[140:143], v[210:213], v[8:11]
	v_mfma_f32_16x16x32_bf16 v[12:15], v[132:135], v[210:213], v[12:15]
	v_mfma_f32_16x16x32_bf16 v[12:15], v[128:131], v[206:209], v[12:15]
	s_barrier
	s_add_i32 s57, s57, 2
	s_add_u32 s8, s8, 0x100
	s_addc_u32 s9, s9, 0
	s_add_u32 s55, s55, 0x100
	s_addc_u32 s56, s56, 0
	s_cmp_gt_u32 s57, 61
	s_cbranch_scc0 .LBB0_986
	s_and_b64 vcc, exec, s[12:13]
	s_cbranch_vccz .LBB0_989
	s_barrier
